# speedup vs baseline: 1.0070x; 1.0014x over previous
; #define SBAR() __builtin_amdgcn_sched_barrier(0)
; #define HBAR(n) do { asm volatile("s_waitcnt vmcnt(" #n ") lgkmcnt(0)" ::: "memory"); __builtin_amdgcn_s_barrier(); asm volatile("" ::: "memory"); } while (0)
; #define RD2(S, k, D0) do { S##l##k = tr_read<v_rd_off(D0, k, 0)>(vb); S##h##k = tr_read<v_rd_off(D0, k, 1)>(vb); } while (0)
; #define PVB(X, Y, D0, D1) do { LW(6); MF(X, 0, D0, pa0); SBAR(); RD2(Y, 0, D1); LW(6); MF(X, 1, D0, pa1); SBAR(); RD2(Y, 1, D1); \
;     LW(6); MF(X, 2, D0, pa2); SBAR(); RD2(Y, 2, D1); LW(6); MF(X, 3, D0, pa3); SBAR(); RD2(Y, 3, D1); } while (0)
; __device__ __forceinline__ void finishSM(f32x16& p0, f32x16& p1, float alpha, float& l_reg, bf16x8& pa0, bf16x8& pa1, bf16x8& pa2, bf16x8& pa3) {
;     ...
;     PK4(p0, 0, pa0); PK4(p0, 8, pa1); PK4(p1, 0, pa2); PK4(p1, 8, pa3);
; __device__ __forceinline__ void attn_dense_body(const bf16_t* __restrict__ Qb, const bf16_t* __restrict__ Kh, const bf16_t* __restrict__ Vh,
;                                                 float* __restrict__ Ob, int seq, char* lds, LAS unsigned char* lds3, const int tid) {
;     ...
;         const int vb = vb0 + b * (int)SHM_V;
;         s16x4 Al0, Ah0, Al1, Ah1, Al2, Ah2, Al3, Ah3, Bl0, Bh0, Bl1, Bh1, Bl2, Bh2, Bl3, Bh3;
;     ...
;         HBAR(6);
;         SBAR();
;         {
;     ...
;           __builtin_amdgcn_s_setprio(1);
;           RD2(A, 0, 0); RD2(A, 1, 0); RD2(A, 2, 0); RD2(A, 3, 0);
;           PVB(A, B, 0, 1); PVB(B, A, 1, 2); PVB(A, B, 2, 3); PVB(B, A, 3, 4); PVB(A, B, 4, 5); PVB(B, A, 5, 6); PVB(A, B, 6, 7);
.Lat_cont:
	v_add_f32_e32 v245, v245, v0
	v_add_f32_e32 v229, v229, v14
	v_cvt_pk_bf16_f32 v2, v160, v161
	v_cvt_pk_bf16_f32 v3, v162, v163
	v_cvt_pk_bf16_f32 v4, v168, v169
	v_cvt_pk_bf16_f32 v5, v170, v171
	v_cvt_pk_bf16_f32 v6, v176, v177
	v_cvt_pk_bf16_f32 v7, v178, v179
	v_cvt_pk_bf16_f32 v8, v184, v185
	v_cvt_pk_bf16_f32 v9, v186, v187
	v_cvt_pk_bf16_f32 v10, v164, v165
	v_cvt_pk_bf16_f32 v11, v166, v167
	v_cvt_pk_bf16_f32 v12, v172, v173
	v_cvt_pk_bf16_f32 v13, v174, v175
	v_cvt_pk_bf16_f32 v152, v180, v181
	v_cvt_pk_bf16_f32 v153, v182, v183
	v_cvt_pk_bf16_f32 v154, v188, v189
	v_cvt_pk_bf16_f32 v155, v190, v191
	v_lshl_add_u32 v14, s91, 15, v247
	ds_read_b64_tr_b16 v[160:161], v14 offset:0
	ds_read_b64_tr_b16 v[162:163], v14 offset:8192
	ds_read_b64_tr_b16 v[164:165], v14 offset:256
	ds_read_b64_tr_b16 v[166:167], v14 offset:8448
	ds_read_b64_tr_b16 v[168:169], v14 offset:512
	ds_read_b64_tr_b16 v[170:171], v14 offset:8704
	ds_read_b64_tr_b16 v[172:173], v14 offset:768
	ds_read_b64_tr_b16 v[174:175], v14 offset:8960
	ds_read_b64_tr_b16 v[176:177], v14 offset:1024
	ds_read_b64_tr_b16 v[178:179], v14 offset:9216
	ds_read_b64_tr_b16 v[180:181], v14 offset:1280
	ds_read_b64_tr_b16 v[182:183], v14 offset:9472
	v_lshl_add_u32 v232, s99, 14, v246
	v_add_u32_e32 v0, v239, v232
	v_xad_u32 v15, v239, 64, v232
	v_xad_u32 v231, v239, s60, v232
	s_movk_i32 s0, 0xc0
	v_xad_u32 v232, v239, s0, v232
	s_waitcnt vmcnt(6) lgkmcnt(0)
	s_barrier
	s_setprio 1
	ds_read_b64_tr_b16 v[184:185], v14 offset:1536
	ds_read_b64_tr_b16 v[186:187], v14 offset:9728
	ds_read_b64_tr_b16 v[188:189], v14 offset:1792
	ds_read_b64_tr_b16 v[190:191], v14 offset:9984
	v_mfma_f32_16x16x32_bf16 v[16:19], v[2:5], v[160:163], v[16:19]
	v_mfma_f32_16x16x32_bf16 v[80:83], v[10:13], v[160:163], v[80:83]
	v_mfma_f32_16x16x32_bf16 v[20:23], v[2:5], v[164:167], v[20:23]
	ds_read_b64_tr_b16 v[160:161], v14 offset:16384
	v_mfma_f32_16x16x32_bf16 v[84:87], v[10:13], v[164:167], v[84:87]
	ds_read_b64_tr_b16 v[162:163], v14 offset:24576
	v_mfma_f32_16x16x32_bf16 v[24:27], v[2:5], v[168:171], v[24:27]
	ds_read_b64_tr_b16 v[164:165], v14 offset:16640
	v_mfma_f32_16x16x32_bf16 v[88:91], v[10:13], v[168:171], v[88:91]
	ds_read_b64_tr_b16 v[166:167], v14 offset:24832
	v_mfma_f32_16x16x32_bf16 v[28:31], v[2:5], v[172:175], v[28:31]
	ds_read_b64_tr_b16 v[168:169], v14 offset:16896
	v_mfma_f32_16x16x32_bf16 v[92:95], v[10:13], v[172:175], v[92:95]
	ds_read_b64_tr_b16 v[170:171], v14 offset:25088
	v_mfma_f32_16x16x32_bf16 v[32:35], v[2:5], v[176:179], v[32:35]
	ds_read_b64_tr_b16 v[172:173], v14 offset:17152
	v_mfma_f32_16x16x32_bf16 v[96:99], v[10:13], v[176:179], v[96:99]
	ds_read_b64_tr_b16 v[174:175], v14 offset:25344
	v_mfma_f32_16x16x32_bf16 v[36:39], v[2:5], v[180:183], v[36:39]
	ds_read_b64_tr_b16 v[176:177], v14 offset:17408
	v_mfma_f32_16x16x32_bf16 v[100:103], v[10:13], v[180:183], v[100:103]
	ds_read_b64_tr_b16 v[178:179], v14 offset:25600
	s_waitcnt lgkmcnt(10)
	v_mfma_f32_16x16x32_bf16 v[40:43], v[2:5], v[184:187], v[40:43]
	ds_read_b64_tr_b16 v[180:181], v14 offset:17664
	v_mfma_f32_16x16x32_bf16 v[104:107], v[10:13], v[184:187], v[104:107]
	ds_read_b64_tr_b16 v[182:183], v14 offset:25856
	v_mfma_f32_16x16x32_bf16 v[44:47], v[2:5], v[188:191], v[44:47]
	ds_read_b64_tr_b16 v[184:185], v14 offset:17920
	v_mfma_f32_16x16x32_bf16 v[108:111], v[10:13], v[188:191], v[108:111]
	ds_read_b64_tr_b16 v[186:187], v14 offset:26112
	s_waitcnt lgkmcnt(10)
	v_mfma_f32_16x16x32_bf16 v[16:19], v[6:9], v[160:163], v[16:19]
	ds_read_b64_tr_b16 v[188:189], v14 offset:18176
	v_mfma_f32_16x16x32_bf16 v[80:83], v[152:155], v[160:163], v[80:83]
	ds_read_b64_tr_b16 v[190:191], v14 offset:26368
	v_mfma_f32_16x16x32_bf16 v[20:23], v[6:9], v[164:167], v[20:23]
	ds_read_b64_tr_b16 v[160:161], v14 offset:2048
	v_mfma_f32_16x16x32_bf16 v[84:87], v[152:155], v[164:167], v[84:87]
	ds_read_b64_tr_b16 v[162:163], v14 offset:10240
	s_waitcnt lgkmcnt(10)
	v_mfma_f32_16x16x32_bf16 v[24:27], v[6:9], v[168:171], v[24:27]
	ds_read_b64_tr_b16 v[164:165], v14 offset:18432
	v_mfma_f32_16x16x32_bf16 v[88:91], v[152:155], v[168:171], v[88:91]
	ds_read_b64_tr_b16 v[166:167], v14 offset:26624
	v_mfma_f32_16x16x32_bf16 v[28:31], v[6:9], v[172:175], v[28:31]
	ds_read_b64_tr_b16 v[168:169], v14 offset:2304
	v_mfma_f32_16x16x32_bf16 v[92:95], v[152:155], v[172:175], v[92:95]
	ds_read_b64_tr_b16 v[170:171], v14 offset:10496
	s_waitcnt lgkmcnt(10)
	v_mfma_f32_16x16x32_bf16 v[32:35], v[6:9], v[176:179], v[32:35]
	ds_read_b64_tr_b16 v[172:173], v14 offset:18688
	v_mfma_f32_16x16x32_bf16 v[96:99], v[152:155], v[176:179], v[96:99]
	ds_read_b64_tr_b16 v[174:175], v14 offset:26880
	v_mfma_f32_16x16x32_bf16 v[36:39], v[6:9], v[180:183], v[36:39]
	ds_read_b64_tr_b16 v[176:177], v14 offset:2560
	v_mfma_f32_16x16x32_bf16 v[100:103], v[152:155], v[180:183], v[100:103]
	ds_read_b64_tr_b16 v[178:179], v14 offset:10752
	s_waitcnt lgkmcnt(10)
	v_mfma_f32_16x16x32_bf16 v[40:43], v[6:9], v[184:187], v[40:43]
	ds_read_b64_tr_b16 v[180:181], v14 offset:18944
	v_mfma_f32_16x16x32_bf16 v[104:107], v[152:155], v[184:187], v[104:107]
	ds_read_b64_tr_b16 v[182:183], v14 offset:27136
	v_mfma_f32_16x16x32_bf16 v[44:47], v[6:9], v[188:191], v[44:47]
	ds_read_b64_tr_b16 v[184:185], v14 offset:2816
	v_mfma_f32_16x16x32_bf16 v[108:111], v[152:155], v[188:191], v[108:111]
	ds_read_b64_tr_b16 v[186:187], v14 offset:11008
	s_waitcnt lgkmcnt(10)
; #define SBAR() __builtin_amdgcn_sched_barrier(0)
; #define KM(d0, B0, B1) do { p0 = __builtin_amdgcn_mfma_f32_32x32x16_bf16(B0, qr[d0], p0, 0, 0, 0); p1 = __builtin_amdgcn_mfma_f32_32x32x16_bf16(B1, qr[d0], p1, 0, 0, 0); } while (0)
; #define HBAR(n) do { asm volatile("s_waitcnt vmcnt(" #n ") lgkmcnt(0)" ::: "memory"); __builtin_amdgcn_s_barrier(); asm volatile("" ::: "memory"); } while (0)
; #define LW(n) do { asm volatile("s_waitcnt lgkmcnt(" #n ")" ::: "memory"); SBAR(); } while (0)
; #define RD2(S, k, D0) do { S##l##k = tr_read<v_rd_off(D0, k, 0)>(vb); S##h##k = tr_read<v_rd_off(D0, k, 1)>(vb); } while (0)
; #define LW(n) do { asm volatile("s_waitcnt lgkmcnt(" #n ")" ::: "memory"); SBAR(); } while (0)
; __device__ __forceinline__ void attn_dense_body(const bf16_t* __restrict__ Qb, const bf16_t* __restrict__ Kh, const bf16_t* __restrict__ Vh,
;                                                 float* __restrict__ Ob, int seq, char* lds, LAS unsigned char* lds3, const int tid) {
;     ...
;           __builtin_amdgcn_s_setprio(1);
;           RD2(A, 0, 0); RD2(A, 1, 0); RD2(A, 2, 0); RD2(A, 3, 0);
;           PVB(A, B, 0, 1); PVB(B, A, 1, 2); PVB(A, B, 2, 3); PVB(B, A, 3, 4); PVB(A, B, 4, 5); PVB(B, A, 5, 6); PVB(A, B, 6, 7);
;           const int kadr = (int)(uintptr_t)K_lds + b1 * (int)SHM_K + r32 * 256; int kt = (hi * 16) ^ ((r32 & 7) << 4);
;           asm volatile("" : "+v"(kt));
;           bf16x8 k0a, k0b, k1a, k1b, k2a, k2b;
;     ...
;           LW(6); MF(B, 0, 7, pa0); SBAR(); KRD(0, k0a, k0b);
;           LW(6); MF(B, 1, 7, pa1); SBAR(); KRD(1, k1a, k1b);
;           LW(6); MF(B, 2, 7, pa2); SBAR(); KRD(2, k2a, k2b);
;           LW(6); MF(B, 3, 7, pa3); SBAR();
;           LW(4); p0 = __builtin_amdgcn_mfma_f32_32x32x16_bf16(k0a, qr[0], nm, 0, 0, 0); p1 = __builtin_amdgcn_mfma_f32_32x32x16_bf16(k0b, qr[0], nm, 0, 0, 0); SBAR(); KRD(3, k0a, k0b);
;           LW(4); KM(1, k1a, k1b); SBAR(); KRD(4, k1a, k1b);
;           LW(4); KM(2, k2a, k2b); SBAR(); KRD(5, k2a, k2b);
;           LW(4); KM(3, k0a, k0b); SBAR(); KRD(6, k0a, k0b);
;           LW(4); KM(4, k1a, k1b); SBAR(); KRD(7, k1a, k1b);
;           LW(4); KM(5, k2a, k2b); SBAR();
;           LW(2); KM(6, k0a, k0b); SBAR();
;           LW(0); KM(7, k1a, k1b);
;           __builtin_amdgcn_s_setprio(0);
;     ...
;         }
;     ...
;         HBAR(0);
;         { const int t_ = b; b = b1; b1 = b2; b2 = t_; }
	v_mfma_f32_16x16x32_bf16 v[48:51], v[2:5], v[160:163], v[48:51]
	ds_read_b64_tr_b16 v[188:189], v14 offset:19200
	v_mfma_f32_16x16x32_bf16 v[112:115], v[10:13], v[160:163], v[112:115]
	ds_read_b64_tr_b16 v[190:191], v14 offset:27392
	v_mfma_f32_16x16x32_bf16 v[48:51], v[6:9], v[164:167], v[48:51]
	ds_read_b64_tr_b16 v[160:161], v14 offset:3072
	v_mfma_f32_16x16x32_bf16 v[112:115], v[152:155], v[164:167], v[112:115]
	ds_read_b64_tr_b16 v[162:163], v14 offset:11264
	s_waitcnt lgkmcnt(10)
	v_mfma_f32_16x16x32_bf16 v[52:55], v[2:5], v[168:171], v[52:55]
	ds_read_b64_tr_b16 v[164:165], v14 offset:19456
	v_mfma_f32_16x16x32_bf16 v[116:119], v[10:13], v[168:171], v[116:119]
	ds_read_b64_tr_b16 v[166:167], v14 offset:27648
	v_mfma_f32_16x16x32_bf16 v[52:55], v[6:9], v[172:175], v[52:55]
	ds_read_b64_tr_b16 v[168:169], v14 offset:3328
	v_mfma_f32_16x16x32_bf16 v[116:119], v[152:155], v[172:175], v[116:119]
	ds_read_b64_tr_b16 v[170:171], v14 offset:11520
	s_waitcnt lgkmcnt(10)
	v_mfma_f32_16x16x32_bf16 v[56:59], v[2:5], v[176:179], v[56:59]
	ds_read_b64_tr_b16 v[172:173], v14 offset:19712
	v_mfma_f32_16x16x32_bf16 v[120:123], v[10:13], v[176:179], v[120:123]
	ds_read_b64_tr_b16 v[174:175], v14 offset:27904
	v_mfma_f32_16x16x32_bf16 v[56:59], v[6:9], v[180:183], v[56:59]
	ds_read_b64_tr_b16 v[176:177], v14 offset:3584
	v_mfma_f32_16x16x32_bf16 v[120:123], v[152:155], v[180:183], v[120:123]
	ds_read_b64_tr_b16 v[178:179], v14 offset:11776
	s_waitcnt lgkmcnt(10)
	v_mfma_f32_16x16x32_bf16 v[60:63], v[2:5], v[184:187], v[60:63]
	ds_read_b64_tr_b16 v[180:181], v14 offset:19968
	v_mfma_f32_16x16x32_bf16 v[124:127], v[10:13], v[184:187], v[124:127]
	ds_read_b64_tr_b16 v[182:183], v14 offset:28160
	v_mfma_f32_16x16x32_bf16 v[60:63], v[6:9], v[188:191], v[60:63]
	ds_read_b64_tr_b16 v[184:185], v14 offset:3840
	v_mfma_f32_16x16x32_bf16 v[124:127], v[152:155], v[188:191], v[124:127]
	ds_read_b64_tr_b16 v[186:187], v14 offset:12032
	s_waitcnt lgkmcnt(10)
	v_mfma_f32_16x16x32_bf16 v[64:67], v[2:5], v[160:163], v[64:67]
	ds_read_b64_tr_b16 v[188:189], v14 offset:20224
	v_mfma_f32_16x16x32_bf16 v[128:131], v[10:13], v[160:163], v[128:131]
	ds_read_b64_tr_b16 v[190:191], v14 offset:28416
	v_mfma_f32_16x16x32_bf16 v[64:67], v[6:9], v[164:167], v[64:67]
	v_mfma_f32_16x16x32_bf16 v[128:131], v[152:155], v[164:167], v[128:131]
	s_waitcnt lgkmcnt(8)
	v_mfma_f32_16x16x32_bf16 v[68:71], v[2:5], v[168:171], v[68:71]
	v_mfma_f32_16x16x32_bf16 v[132:135], v[10:13], v[168:171], v[132:135]
	v_mfma_f32_16x16x32_bf16 v[68:71], v[6:9], v[172:175], v[68:71]
	v_mfma_f32_16x16x32_bf16 v[132:135], v[152:155], v[172:175], v[132:135]
	s_waitcnt lgkmcnt(4)
	v_mfma_f32_16x16x32_bf16 v[72:75], v[2:5], v[176:179], v[72:75]
	v_mfma_f32_16x16x32_bf16 v[136:139], v[10:13], v[176:179], v[136:139]
	ds_read_b128 v[156:159], v0 offset:0
	v_mfma_f32_16x16x32_bf16 v[72:75], v[6:9], v[180:183], v[72:75]
	v_mfma_f32_16x16x32_bf16 v[136:139], v[152:155], v[180:183], v[136:139]
	ds_read_b128 v[224:227], v15 offset:0
	s_waitcnt lgkmcnt(2)
	v_mfma_f32_16x16x32_bf16 v[76:79], v[2:5], v[184:187], v[76:79]
	v_mfma_f32_16x16x32_bf16 v[140:143], v[10:13], v[184:187], v[140:143]
	ds_read_b128 v[234:237], v231 offset:0
	v_mfma_f32_16x16x32_bf16 v[76:79], v[6:9], v[188:191], v[76:79]
	v_mfma_f32_16x16x32_bf16 v[140:143], v[152:155], v[188:191], v[140:143]
	ds_read_b128 v[248:251], v232 offset:0
	ds_read_b128 v[2:5], v0 offset:4096
	ds_read_b128 v[6:9], v15 offset:4096
	ds_read_b128 v[10:13], v231 offset:4096
	ds_read_b128 v[152:155], v232 offset:4096
	s_waitcnt lgkmcnt(7)
	v_mfma_f32_16x16x32_bf16 v[160:163], v[156:159], v[192:195], v[144:147]
	v_mfma_f32_16x16x32_bf16 v[164:167], v[156:159], v[208:211], v[148:151]
	ds_read_b128 v[156:159], v0 offset:8192
	s_waitcnt lgkmcnt(7)
	v_mfma_f32_16x16x32_bf16 v[160:163], v[224:227], v[196:199], v[160:163]
	v_mfma_f32_16x16x32_bf16 v[164:167], v[224:227], v[212:215], v[164:167]
	ds_read_b128 v[224:227], v15 offset:8192
	s_waitcnt lgkmcnt(7)
	v_mfma_f32_16x16x32_bf16 v[160:163], v[234:237], v[200:203], v[160:163]
	v_mfma_f32_16x16x32_bf16 v[164:167], v[234:237], v[216:219], v[164:167]
	ds_read_b128 v[234:237], v231 offset:8192
	s_waitcnt lgkmcnt(7)
	v_mfma_f32_16x16x32_bf16 v[160:163], v[248:251], v[204:207], v[160:163]
	v_mfma_f32_16x16x32_bf16 v[164:167], v[248:251], v[220:223], v[164:167]
	ds_read_b128 v[248:251], v232 offset:8192
	s_waitcnt lgkmcnt(7)
	v_mfma_f32_16x16x32_bf16 v[168:171], v[2:5], v[192:195], v[144:147]
	v_mfma_f32_16x16x32_bf16 v[172:175], v[2:5], v[208:211], v[148:151]
	ds_read_b128 v[2:5], v0 offset:12288
	s_waitcnt lgkmcnt(7)
	v_mfma_f32_16x16x32_bf16 v[168:171], v[6:9], v[196:199], v[168:171]
	v_mfma_f32_16x16x32_bf16 v[172:175], v[6:9], v[212:215], v[172:175]
	ds_read_b128 v[6:9], v15 offset:12288
	s_waitcnt lgkmcnt(7)
	v_mfma_f32_16x16x32_bf16 v[168:171], v[10:13], v[200:203], v[168:171]
	v_mfma_f32_16x16x32_bf16 v[172:175], v[10:13], v[216:219], v[172:175]
	ds_read_b128 v[10:13], v231 offset:12288
	s_waitcnt lgkmcnt(7)
	v_mfma_f32_16x16x32_bf16 v[168:171], v[152:155], v[204:207], v[168:171]
	v_mfma_f32_16x16x32_bf16 v[172:175], v[152:155], v[220:223], v[172:175]
	ds_read_b128 v[152:155], v232 offset:12288
	s_waitcnt lgkmcnt(7)
	v_mfma_f32_16x16x32_bf16 v[176:179], v[156:159], v[192:195], v[144:147]
	v_mfma_f32_16x16x32_bf16 v[180:183], v[156:159], v[208:211], v[148:151]
	s_waitcnt lgkmcnt(6)
	v_mfma_f32_16x16x32_bf16 v[176:179], v[224:227], v[196:199], v[176:179]
	v_mfma_f32_16x16x32_bf16 v[180:183], v[224:227], v[212:215], v[180:183]
	s_waitcnt lgkmcnt(5)
	v_mfma_f32_16x16x32_bf16 v[176:179], v[234:237], v[200:203], v[176:179]
	v_mfma_f32_16x16x32_bf16 v[180:183], v[234:237], v[216:219], v[180:183]
	s_waitcnt lgkmcnt(4)
	v_mfma_f32_16x16x32_bf16 v[176:179], v[248:251], v[204:207], v[176:179]
	v_mfma_f32_16x16x32_bf16 v[180:183], v[248:251], v[220:223], v[180:183]
	s_waitcnt lgkmcnt(3)
	v_mfma_f32_16x16x32_bf16 v[184:187], v[2:5], v[192:195], v[144:147]
	v_mfma_f32_16x16x32_bf16 v[188:191], v[2:5], v[208:211], v[148:151]
	s_waitcnt lgkmcnt(2)
	v_mfma_f32_16x16x32_bf16 v[184:187], v[6:9], v[196:199], v[184:187]
	v_mfma_f32_16x16x32_bf16 v[188:191], v[6:9], v[212:215], v[188:191]
	s_waitcnt lgkmcnt(1)
	v_mfma_f32_16x16x32_bf16 v[184:187], v[10:13], v[200:203], v[184:187]
	v_mfma_f32_16x16x32_bf16 v[188:191], v[10:13], v[216:219], v[188:191]
	s_waitcnt lgkmcnt(0)
	v_mfma_f32_16x16x32_bf16 v[184:187], v[152:155], v[204:207], v[184:187]
	v_mfma_f32_16x16x32_bf16 v[188:191], v[152:155], v[220:223], v[188:191]
	s_setprio 0
	s_waitcnt vmcnt(0) lgkmcnt(0)
	s_barrier
	s_cmp_eq_u32 s15, s89
	s_cbranch_scc1 .Lat_done
	s_mov_b32 s0, s99
	s_mov_b32 s99, s10
	s_mov_b32 s10, s91
	s_branch .Lat_loop
